# s5_out set-up: WC fragment loads made lane-linear (1 KiB per wave instruction) and transposed through a private padded LDS region
# speedup vs baseline: 1.0030x; 1.0006x over previous
; #define LAS __attribute__((address_space(3)))
; #define LBAR() do { asm volatile("s_waitcnt lgkmcnt(0)" ::: "memory"); __builtin_amdgcn_s_barrier(); asm volatile("" ::: "memory"); } while (0)
; __device__ __forceinline__ void s5_out_block2(LAS unsigned char* lds, const bf16* __restrict__ MLAG, const bf16* __restrict__ WC, const bf16* __restrict__ HP, const bf16* __restrict__ U, ...
;     constexpr int UOFF = 16384, UROW = 1040, HOFF = UOFF + 32 * UROW, HROW = 272;
;     const int g = vb >> 2;
;     const int r = lane & 31, h = lane >> 5, rj = r >> 4, rp = r & 15;
;     LBAR();
;     { const u32x4* src = (const u32x4*)(MLAG + (size_t)g * 8192); LAS u32x4* dst = (LAS u32x4*)lds; dst[tid] = src[tid]; dst[tid + 512] = src[tid + 512]; }
; __global__ void __launch_bounds__(512, 2) mega(Args a) {
;     ...
;             const int g = b >> 2;
;             if (tid == 0) { unsigned sp = 0; while (__hip_atomic_load(flg + 64 * g, __ATOMIC_RELAXED, __HIP_MEMORY_SCOPE_AGENT) == 0u) { __builtin_amdgcn_s_sleep(4); if (++sp > (1u << 22)) break; }
;                 __builtin_amdgcn_fence(__ATOMIC_ACQUIRE, "agent"); asm volatile("s_waitcnt vmcnt(0)" ::: "memory"); }
;             __syncthreads();
;             s5_out_block2(lds, MLAG, WC, HP, Ub, a.in[10], Yb, b, tid, wave, lane);
.LBB0_803:
	s_or_b64 exec, exec, s[0:1]
	s_ashr_i32 s4, s66, 2
	s_ashr_i32 s5, s4, 31
	s_lshl_b64 s[0:1], s[4:5], 14
	v_readlane_b32 s2, v245, 30
	v_readlane_b32 s3, v245, 31
	s_add_u32 s6, s2, s0
	s_addc_u32 s7, s3, s1
	s_waitcnt vmcnt(18)
	v_mov_b32_e32 v153, 0
	v_lshlrev_b32_e32 v152, 4, v186
	v_lshl_add_u64 v[4:5], s[6:7], 0, v[152:153]
	s_movk_i32 s8, 0x2000
	v_add_co_u32_e32 v4, vcc, s8, v4
	s_barrier
	s_waitcnt lgkmcnt(0)
	s_barrier
; #define LAS __attribute__((address_space(3)))
; #define S5O_PREFETCH(ctv) do { const u32x4* us_ = (const u32x4*)(U + ((size_t)g * S + (size_t)(ctv) * 1024) * 16); _Pragma("unroll") for (int i_ = 0; i_ < 4; ++i_) su[i_] = us_[tid + 512 * i_]; \
;         sh = ((const u32x4*)(HP + ((size_t)g * SNC + (ctv) * 32) * 128))[tid]; } while (0)
; __device__ __forceinline__ void s5_out_block2(LAS unsigned char* lds, const bf16* __restrict__ MLAG, const bf16* __restrict__ WC, const bf16* __restrict__ HP, const bf16* __restrict__ U, ...
;     ...
;     const LAS unsigned char* ml = lds + rp * 32 + h * 16;
;     const LAS unsigned char* ul = lds + UOFF + r * UROW + h * 16;
;     const LAS unsigned char* hl = lds + HOFF + r * HROW + h * 16;
;     const f32x4 dA = *(const f32x4*)(d_skip + g * 16 + 4 * h), dB = *(const f32x4*)(d_skip + g * 16 + 8 + 4 * h);
;     bf16x8 wc[2][8];
; #pragma unroll
;     for (int q = 0; q < 2; ++q) { const int jj = q ? 15 - wave : wave; const bf16* wcb = WC + ((size_t)g * 512 + jj * 32 + r) * 128 + 8 * h;
; #pragma unroll
;         for (int ks = 0; ks < 8; ++ks) wc[q][ks] = *(const bf16x8*)(wcb + 16 * ks); }
;     u32x4 su[4], sh;
;     ...
;     S5O_PREFETCH(4 * (vb & 3));
	v_addc_co_u32_e32 v5, vcc, 0, v5, vcc
	global_load_dwordx4 v[0:3], v152, s[6:7]
	v_lshrrev_b32_e32 v17, 5, v184
	global_load_dwordx4 v[4:7], v[4:5], off
	s_lshl_b32 s6, s4, 4
	s_ashr_i32 s7, s6, 31
	s_lshl_b64 s[16:17], s[6:7], 2
	s_add_u32 s16, s76, s16
	v_and_b32_e32 v16, 31, v186
	v_lshlrev_b32_e32 v8, 4, v17
	s_addc_u32 s17, s77, s17
	s_lshl_b64 s[4:5], s[4:5], 9
	s_mov_b32 s3, 0
	global_load_dwordx4 v[32:35], v8, s[16:17]
	global_load_dwordx4 v[36:39], v8, s[16:17] offset:32
	v_or_b32_e32 v10, s4, v16
	v_mov_b32_e32 v11, s5
	v_readlane_b32 s16, v245, 32
	s_lshl_b32 s2, s65, 5
	s_sub_i32 s20, 15, s65
	v_mov_b32_e32 v9, v153
	v_readlane_b32 s17, v245, 33
	v_lshl_add_u64 v[14:15], v[10:11], 0, s[2:3]
	s_lshl_b32 s2, s66, 2
	v_lshl_add_u64 v[12:13], s[16:17], 0, v[8:9]
	s_lshl_b32 s16, s20, 5
	s_and_b32 s2, s2, 12
	s_ashr_i32 s17, s16, 31
	s_lshl_b32 s9, s2, 10
	v_lshl_add_u64 v[10:11], v[10:11], 0, s[16:17]
	s_or_b32 s16, s0, s9
	s_mov_b32 s17, s1
	s_lshl_b64 s[16:17], s[16:17], 5
	s_add_u32 s16, s86, s16
	v_lshlrev_b64 v[14:15], 8, v[14:15]
	v_lshlrev_b64 v[10:11], 8, v[10:11]
	s_addc_u32 s17, s87, s17
	v_lshl_add_u64 v[14:15], v[12:13], 0, v[14:15]
	v_lshl_add_u64 v[10:11], v[12:13], 0, v[10:11]
	v_lshl_add_u64 v[12:13], s[16:17], 0, v[152:153]
	v_readlane_b32 s36, v245, 32
	v_readlane_b32 s37, v245, 33
	s_ashr_i32 s38, s66, 2
	s_lshl_b32 s38, s38, 9
	s_lshl_b32 s39, s65, 5
	s_add_i32 s40, s38, s39
	s_sub_i32 s39, 15, s65
	s_lshl_b32 s39, s39, 5
	s_add_i32 s41, s38, s39
	s_lshl_b32 s40, s40, 8
	s_lshl_b32 s41, s41, 8
	v_lshlrev_b32_e32 v223, 4, v184
	v_add_u32_e32 v225, s41, v223
	v_add_u32_e32 v223, s40, v223
	v_add_u32_e32 v224, 0x1000, v223
	v_add_u32_e32 v226, 0x1000, v225
	global_load_dwordx4 v[40:43], v223, s[36:37]
	global_load_dwordx4 v[44:47], v223, s[36:37] offset:1024
	global_load_dwordx4 v[48:51], v223, s[36:37] offset:2048
	global_load_dwordx4 v[52:55], v223, s[36:37] offset:3072
	global_load_dwordx4 v[56:59], v224, s[36:37]
	global_load_dwordx4 v[60:63], v224, s[36:37] offset:1024
	global_load_dwordx4 v[64:67], v224, s[36:37] offset:2048
	global_load_dwordx4 v[68:71], v224, s[36:37] offset:3072
	global_load_dwordx4 v[72:75], v225, s[36:37]
	global_load_dwordx4 v[76:79], v225, s[36:37] offset:1024
	global_load_dwordx4 v[80:83], v225, s[36:37] offset:2048
	global_load_dwordx4 v[84:87], v225, s[36:37] offset:3072
	global_load_dwordx4 v[88:91], v226, s[36:37]
	global_load_dwordx4 v[92:95], v226, s[36:37] offset:1024
	global_load_dwordx4 v[96:99], v226, s[36:37] offset:2048
	v_add_co_u32_e32 v14, vcc, s8, v12
	global_load_dwordx4 v[104:107], v152, s[16:17]
	s_nop 0
	v_addc_co_u32_e32 v15, vcc, 0, v13, vcc
	global_load_dwordx4 v[100:103], v226, s[36:37] offset:3072
	global_load_dwordx4 v[108:111], v[14:15], off
	v_or_b32_e32 v10, 0x400, v186
	s_movk_i32 s9, 0x6000
	v_lshlrev_b32_e32 v11, 4, v10
	v_add_co_u32_e32 v12, vcc, s9, v12
	v_lshl_add_u64 v[154:155], s[14:15], 0, v[152:153]
	s_nop 0
	v_addc_co_u32_e32 v13, vcc, 0, v13, vcc
	global_load_dwordx4 v[112:115], v11, s[16:17]
	global_load_dwordx4 v[116:119], v[12:13], off
	s_lshl_b32 s16, s2, 5
	s_or_b32 s16, s4, s16
	s_mov_b32 s17, s5
	s_lshl_b64 s[16:17], s[16:17], 8
	s_add_u32 s16, s14, s16
	s_addc_u32 s17, s15, s17
	global_load_dwordx4 v[120:123], v152, s[16:17]
	v_add_u32_e32 v11, 0, v152
	s_lshl_b64 s[6:7], s[6:7], 1
	s_movk_i32 s14, 0x110
	s_add_u32 s6, s12, s6
	s_movk_i32 s16, 0x410
	s_addc_u32 s7, s13, s7
	s_waitcnt vmcnt(42)
	v_lshl_add_u64 v[156:157], s[6:7], 0, v[8:9]
	v_readlane_b32 s6, v245, 1
	s_lshl_b32 s18, s20, 1
	v_lshrrev_b32_e32 v9, 6, v10
	v_mul_u32_u24_e32 v9, 0x410, v9
	s_waitcnt vmcnt(41)
	v_bfe_u32 v160, v186, 4, 1
	v_lshlrev_b32_e32 v162, 5, v16
	v_lshlrev_b32_e32 v158, 4, v186
	v_lshlrev_b32_e32 v170, 4, v10
	s_waitcnt vmcnt(24)
	ds_write_b128 v11, v[0:3]
	v_lshlrev_b32_e32 v1, 5, v186
	s_waitcnt vmcnt(23)
	ds_write_b128 v11, v[4:7] offset:8192
	v_lshrrev_b32_e32 v6, 4, v186
	v_mad_u32_u24 v6, v6, s14, 0
	s_lshl_b32 s14, s65, 1
	v_mad_u32_u24 v3, v16, s16, 0
	s_movk_i32 s16, 0xfd00
	s_or_b32 s15, s14, 1
	v_add_u32_e32 v0, 0x200, v186
	v_and_b32_e32 v1, 0x1e0, v1
	v_mad_i32_i24 v4, v16, s16, v3
	v_add_u32_e32 v5, 0x600, v186
	s_and_b32 s16, s6, 0xffffffc0
	s_lshl_b32 s17, s15, 5
	v_mul_u32_u24_e32 v2, 0x410, v16
	v_add3_u32 v161, 0, v1, v8
	v_and_b32_e32 v1, 0x3f0, v152
	v_lshl_add_u32 v163, v17, 3, v3
	v_lshrrev_b32_e32 v3, 6, v186
	v_lshrrev_b32_e32 v0, 6, v0
	v_lshrrev_b32_e32 v5, 6, v5
	s_cmpk_lt_u32 s6, 0x400
	v_add_u32_e32 v1, 0, v1
	v_and_b32_e32 v7, 0xf0, v152
	v_mul_u32_u24_e32 v3, 0x410, v3
	v_mul_u32_u24_e32 v0, 0x410, v0
	v_mul_u32_u24_e32 v5, 0x410, v5
	s_cselect_b64 s[6:7], -1, 0
	s_or_b32 s19, s18, 1
	v_add3_u32 v2, v2, v8, 0
	s_lshl_b32 s20, s20, 6
	s_lshl_b32 s21, s19, 5
	v_add_u32_e32 v164, 0x4000, v2
	s_sub_i32 s22, 29, s14
	v_add_u32_e32 v165, v1, v3
	v_add_u32_e32 v166, v1, v0
	v_add_u32_e32 v167, v1, v9
	v_add_u32_e32 v168, v1, v5
	v_add_u32_e32 v169, v6, v7
	v_add_u32_e32 v171, v4, v8
	s_mul_i32 s38, s65, 0x2200
	s_add_i32 s38, s38, 0xe400
	v_lshrrev_b32_e32 v227, 4, v184
	v_mul_u32_u24_e32 v227, 0x110, v227
	v_and_b32_e32 v187, 15, v184
	v_lshl_add_u32 v227, v187, 4, v227
	v_add_u32_e32 v227, s38, v227
	v_and_b32_e32 v187, 31, v184
	v_mul_u32_u24_e32 v187, 0x110, v187
	v_lshrrev_b32_e32 v222, 5, v184
	v_lshl_add_u32 v187, v222, 4, v187
	v_add_u32_e32 v187, s38, v187
	s_waitcnt vmcnt(0)
	ds_write_b128 v227, v[40:43]
	ds_write_b128 v227, v[44:47] offset:1088
	ds_write_b128 v227, v[48:51] offset:2176
	ds_write_b128 v227, v[52:55] offset:3264
	ds_write_b128 v227, v[56:59] offset:4352
	ds_write_b128 v227, v[60:63] offset:5440
	ds_write_b128 v227, v[64:67] offset:6528
	ds_write_b128 v227, v[68:71] offset:7616
	s_waitcnt lgkmcnt(0)
	ds_read_b128 v[40:43], v187
	ds_read_b128 v[44:47], v187 offset:32
	ds_read_b128 v[48:51], v187 offset:64
	ds_read_b128 v[52:55], v187 offset:96
	ds_read_b128 v[56:59], v187 offset:128
	ds_read_b128 v[60:63], v187 offset:160
	ds_read_b128 v[64:67], v187 offset:192
	ds_read_b128 v[68:71], v187 offset:224
	s_waitcnt lgkmcnt(0)
	ds_write_b128 v227, v[72:75]
	ds_write_b128 v227, v[76:79] offset:1088
	ds_write_b128 v227, v[80:83] offset:2176
	ds_write_b128 v227, v[84:87] offset:3264
	ds_write_b128 v227, v[88:91] offset:4352
	ds_write_b128 v227, v[92:95] offset:5440
	ds_write_b128 v227, v[96:99] offset:6528
	ds_write_b128 v227, v[100:103] offset:7616
	s_waitcnt lgkmcnt(0)
	ds_read_b128 v[72:75], v187
	ds_read_b128 v[76:79], v187 offset:32
	ds_read_b128 v[80:83], v187 offset:64
	ds_read_b128 v[84:87], v187 offset:96
	ds_read_b128 v[88:91], v187 offset:128
	ds_read_b128 v[92:95], v187 offset:160
	ds_read_b128 v[96:99], v187 offset:192
	ds_read_b128 v[100:103], v187 offset:224
	s_waitcnt lgkmcnt(0)
	s_branch .LBB0_805
